# grid barriers: leader adds to TOP before its L1 invalidate and no longer bumps the unread TOPGEN / per-XCD release counters (combined)
# baseline (speedup 1.0000x reference)
; __device__ __forceinline__ unsigned xb_ld(unsigned* p)              { return __hip_atomic_load(p, __ATOMIC_RELAXED, __HIP_MEMORY_SCOPE_AGENT); }
; __device__ __forceinline__ unsigned xb_add(unsigned* p, unsigned v) { return __hip_atomic_fetch_add(p, v, __ATOMIC_RELAXED, __HIP_MEMORY_SCOPE_AGENT); }
; #define XB_SPIN(cond, bar) do { unsigned _sp = 0; while (cond) { __builtin_amdgcn_s_sleep(1); \
;     if ((++_sp & 255u) == 0u) { if (xb_ld(&(bar)[XB_TMO])) break; if (_sp > XB_SPIN_CAP) { atomicAdd(&(bar)[XB_TMO], 1u); break; } } } } while (0)
; __device__ __forceinline__ void xcd_barrier(const XcdBarrier& b) {
;     ...
;             const unsigned og = xb_add(&bar[XB_TOP], 1u);
;             const unsigned tg = og / nx;
;             if (og + 1u == (tg + 1u) * nx) xb_add(&bar[XB_TOPGEN], 1u);
;             else XB_SPIN(xb_ld(&bar[XB_TOPGEN]) == tg, bar);
.LBB0_166:
	s_or_b64 exec, exec, s[10:11]
	buffer_inv sc1
	v_cvt_f32_u32_e32 v3, v0
	s_waitcnt vmcnt(0)
	v_readfirstlane_b32 s8, v2
	s_add_u32 s10, s70, 0x2303500
	s_addc_u32 s11, s71, 0
	v_rcp_iflag_f32_e32 v3, v3
	v_add_u32_e32 v1, s8, v1
	v_add_u32_e32 v4, 1, v1
	s_mov_b64 s[12:13], 0
	v_mul_f32_e32 v2, 0x4f7ffffe, v3
	v_cvt_u32_f32_e32 v2, v2
	v_sub_u32_e32 v3, 0, v0
	v_mul_lo_u32 v3, v3, v2
	v_mul_hi_u32 v3, v2, v3
	v_add_u32_e32 v2, v2, v3
	v_mul_hi_u32 v2, v1, v2
	v_mul_lo_u32 v3, v2, v0
	v_sub_u32_e32 v1, v1, v3
	v_add_u32_e32 v5, 1, v2
	v_cmp_ge_u32_e32 vcc, v1, v0
	v_sub_u32_e32 v3, v1, v0
	s_nop 0
	v_cndmask_b32_e32 v2, v2, v5, vcc
	v_cndmask_b32_e32 v1, v1, v3, vcc
	v_add_u32_e32 v3, 1, v2
	v_cmp_ge_u32_e32 vcc, v1, v0
	s_nop 1
	v_cndmask_b32_e32 v2, v2, v3, vcc
	v_mul_lo_u32 v1, v0, v2
	v_add_u32_e32 v0, v1, v0
	v_cmp_ne_u32_e32 vcc, v4, v0
	v_mov_b32_e32 v3, v0
	v_mov_b32_e32 v5, 0x2303000
	v_mov_b64_e32 v[0:1], s[10:11]
	s_and_saveexec_b64 s[8:9], vcc
	s_cbranch_execz .LBB0_178
	v_mov_b32_e32 v0, 0
	global_load_dword v1, v5, s[70:71] offset:1024 sc1
	s_mov_b64 s[20:21], 0
	s_waitcnt vmcnt(0)
	v_cmp_lt_u32_e32 vcc, v1, v3
	s_and_saveexec_b64 s[18:19], vcc
	s_cbranch_execz .LBB0_177
	s_add_u32 s12, s70, 0x2300200
	s_addc_u32 s13, s71, 0
	s_mov_b32 s14, 1
	s_branch .LBB0_170

; __device__ __forceinline__ unsigned xb_ld(unsigned* p)              { return __hip_atomic_load(p, __ATOMIC_RELAXED, __HIP_MEMORY_SCOPE_AGENT); }
; __device__ __forceinline__ unsigned xb_add(unsigned* p, unsigned v) { return __hip_atomic_fetch_add(p, v, __ATOMIC_RELAXED, __HIP_MEMORY_SCOPE_AGENT); }
; #define XB_SPIN(cond, bar) do { unsigned _sp = 0; while (cond) { __builtin_amdgcn_s_sleep(1); \
;     if ((++_sp & 255u) == 0u) { if (xb_ld(&(bar)[XB_TMO])) break; if (_sp > XB_SPIN_CAP) { atomicAdd(&(bar)[XB_TMO], 1u); break; } } } } while (0)
; __device__ __forceinline__ void xcd_barrier(const XcdBarrier& b) {
;     ...
;             const unsigned og = xb_add(&bar[XB_TOP], 1u);
;             const unsigned tg = og / nx;
;             if (og + 1u == (tg + 1u) * nx) xb_add(&bar[XB_TOPGEN], 1u);
;             else XB_SPIN(xb_ld(&bar[XB_TOPGEN]) == tg, bar);
.LBB0_259:
	s_or_b64 exec, exec, s[8:9]
	buffer_inv sc1
	v_cvt_f32_u32_e32 v3, v0
	s_waitcnt vmcnt(0)
	v_readfirstlane_b32 s6, v2
	s_add_u32 s8, s70, 0x2303500
	s_addc_u32 s9, s71, 0
	v_rcp_iflag_f32_e32 v3, v3
	v_add_u32_e32 v1, s6, v1
	v_add_u32_e32 v4, 1, v1
	s_mov_b64 s[10:11], 0
	v_mul_f32_e32 v2, 0x4f7ffffe, v3
	v_cvt_u32_f32_e32 v2, v2
	v_sub_u32_e32 v3, 0, v0
	v_mul_lo_u32 v3, v3, v2
	v_mul_hi_u32 v3, v2, v3
	v_add_u32_e32 v2, v2, v3
	v_mul_hi_u32 v2, v1, v2
	v_mul_lo_u32 v3, v2, v0
	v_sub_u32_e32 v1, v1, v3
	v_add_u32_e32 v5, 1, v2
	v_cmp_ge_u32_e32 vcc, v1, v0
	v_sub_u32_e32 v3, v1, v0
	s_nop 0
	v_cndmask_b32_e32 v2, v2, v5, vcc
	v_cndmask_b32_e32 v1, v1, v3, vcc
	v_add_u32_e32 v3, 1, v2
	v_cmp_ge_u32_e32 vcc, v1, v0
	s_nop 1
	v_cndmask_b32_e32 v2, v2, v3, vcc
	v_mul_lo_u32 v1, v0, v2
	v_add_u32_e32 v0, v1, v0
	v_cmp_ne_u32_e32 vcc, v4, v0
	v_mov_b32_e32 v3, v0
	v_mov_b32_e32 v5, 0x2303000
	v_mov_b64_e32 v[0:1], s[8:9]
	s_and_saveexec_b64 s[6:7], vcc
	s_cbranch_execz .LBB0_271
	v_mov_b32_e32 v0, 0
	global_load_dword v1, v5, s[70:71] offset:1024 sc1
	s_mov_b64 s[18:19], 0
	s_waitcnt vmcnt(0)
	v_cmp_lt_u32_e32 vcc, v1, v3
	s_and_saveexec_b64 s[12:13], vcc
	s_cbranch_execz .LBB0_270
	s_add_u32 s10, s70, 0x2300200
	s_addc_u32 s11, s71, 0
	s_mov_b32 s14, 1
	s_branch .LBB0_263

; __device__ __forceinline__ unsigned xb_ld(unsigned* p)              { return __hip_atomic_load(p, __ATOMIC_RELAXED, __HIP_MEMORY_SCOPE_AGENT); }
; __device__ __forceinline__ unsigned xb_add(unsigned* p, unsigned v) { return __hip_atomic_fetch_add(p, v, __ATOMIC_RELAXED, __HIP_MEMORY_SCOPE_AGENT); }
; #define XB_SPIN(cond, bar) do { unsigned _sp = 0; while (cond) { __builtin_amdgcn_s_sleep(1); \
;     if ((++_sp & 255u) == 0u) { if (xb_ld(&(bar)[XB_TMO])) break; if (_sp > XB_SPIN_CAP) { atomicAdd(&(bar)[XB_TMO], 1u); break; } } } } while (0)
; __device__ __forceinline__ void xcd_barrier(const XcdBarrier& b) {
;     ...
;             const unsigned og = xb_add(&bar[XB_TOP], 1u);
;             const unsigned tg = og / nx;
;             if (og + 1u == (tg + 1u) * nx) xb_add(&bar[XB_TOPGEN], 1u);
;             else XB_SPIN(xb_ld(&bar[XB_TOPGEN]) == tg, bar);
.LBB0_802:
	s_or_b64 exec, exec, s[10:11]
	buffer_inv sc1
	v_cvt_f32_u32_e32 v3, v0
	s_waitcnt vmcnt(0)
	v_readfirstlane_b32 s3, v2
	s_add_u32 s10, s70, 0x2303500
	s_addc_u32 s11, s71, 0
	v_rcp_iflag_f32_e32 v3, v3
	v_add_u32_e32 v1, s3, v1
	v_add_u32_e32 v4, 1, v1
	s_mov_b64 s[12:13], 0
	v_mul_f32_e32 v2, 0x4f7ffffe, v3
	v_cvt_u32_f32_e32 v2, v2
	v_sub_u32_e32 v3, 0, v0
	v_mul_lo_u32 v3, v3, v2
	v_mul_hi_u32 v3, v2, v3
	v_add_u32_e32 v2, v2, v3
	v_mul_hi_u32 v2, v1, v2
	v_mul_lo_u32 v3, v2, v0
	v_sub_u32_e32 v1, v1, v3
	v_add_u32_e32 v5, 1, v2
	v_cmp_ge_u32_e32 vcc, v1, v0
	v_sub_u32_e32 v3, v1, v0
	s_nop 0
	v_cndmask_b32_e32 v2, v2, v5, vcc
	v_cndmask_b32_e32 v1, v1, v3, vcc
	v_add_u32_e32 v3, 1, v2
	v_cmp_ge_u32_e32 vcc, v1, v0
	s_nop 1
	v_cndmask_b32_e32 v2, v2, v3, vcc
	v_mul_lo_u32 v1, v0, v2
	v_add_u32_e32 v0, v1, v0
	v_cmp_ne_u32_e32 vcc, v4, v0
	v_mov_b32_e32 v3, v0
	v_mov_b32_e32 v5, 0x2303000
	v_mov_b64_e32 v[0:1], s[10:11]
	s_and_saveexec_b64 s[8:9], vcc
	s_cbranch_execz .LBB0_814
	v_mov_b32_e32 v0, 0
	global_load_dword v1, v5, s[70:71] offset:1024 sc1
	s_mov_b64 s[18:19], 0
	s_waitcnt vmcnt(0)
	v_cmp_lt_u32_e32 vcc, v1, v3
	s_and_saveexec_b64 s[14:15], vcc
	s_cbranch_execz .LBB0_813
	s_add_u32 s12, s70, 0x2300200
	s_addc_u32 s13, s71, 0
	s_mov_b32 s3, 1
	s_branch .LBB0_806
